# v18 + P4 loads without nt so the two half-line partner loads of each row merge in L1
# speedup vs baseline: 1.0088x; 1.0088x over previous
.LBB0_409:
	v_lshrrev_b32_e32 v30, 10, v16
	v_lshl_add_u64 v[26:27], v[24:25], 0, v[18:19]
	v_lshl_add_u64 v[28:29], v[22:23], 0, v[18:19]
	v_and_or_b32 v31, v30, s3, v32
	v_lshl_add_u64 v[52:53], v[26:27], 0, s[24:25]
	v_add_co_u32_e32 v30, vcc, s33, v26
	v_lshl_add_u64 v[54:55], v[26:27], 0, s[28:29]
	v_lshl_add_u64 v[56:57], v[28:29], 0, s[30:31]
	global_load_dwordx4 v[40:43], v[52:53], off offset:16
	global_load_dwordx4 v[44:47], v[54:55], off offset:16
	global_load_dwordx4 v[48:51], v[56:57], off offset:16
	v_lshl_or_b32 v52, v31, 14, v33
	v_addc_co_u32_e32 v31, vcc, 0, v27, vcc
	v_add_co_u32_e32 v26, vcc, s36, v26
	v_add_u32_e32 v39, 1, v16
	v_and_or_b32 v70, v16, s17, v52
	v_addc_co_u32_e32 v27, vcc, 0, v27, vcc
	v_lshl_add_u64 v[68:69], v[28:29], 0, s[26:27]
	v_add_co_u32_e32 v28, vcc, s34, v28
	v_and_or_b32 v72, v39, s35, v52
	global_load_dwordx4 v[52:55], v[26:27], off offset:-4096
	global_load_dwordx4 v[56:59], v[26:27], off
	v_ashrrev_i32_e32 v71, 31, v70
	v_addc_co_u32_e32 v29, vcc, 0, v29, vcc
	v_ashrrev_i32_e32 v73, 31, v72
	global_load_dwordx4 v[60:63], v[68:69], off offset:16
	global_load_dwordx4 v[64:67], v[28:29], off
	v_lshlrev_b64 v[74:75], 7, v[70:71]
	v_lshlrev_b64 v[72:73], 7, v[72:73]
	global_load_dwordx4 v[68:71], v[28:29], off offset:2048
	v_lshl_add_u64 v[28:29], v[20:21], 0, v[74:75]
	v_lshl_add_u64 v[88:89], v[20:21], 0, v[72:73]
	global_load_dwordx4 v[72:75], v[28:29], off
	global_load_dwordx4 v[76:79], v[28:29], off offset:16
	global_load_dwordx4 v[80:83], v[88:89], off
	global_load_dwordx4 v[84:87], v[88:89], off offset:16
	v_add_u32_e32 v16, s16, v16
	v_cmp_lt_i32_e32 vcc, s38, v16
	s_or_b64 s[22:23], vcc, s[22:23]
	v_lshl_add_u64 v[22:23], v[22:23], 0, s[18:19]
	v_lshl_add_u64 v[24:25], v[24:25], 0, s[20:21]
	s_waitcnt vmcnt(11)
	v_lshlrev_b32_e32 v88, 16, v43
	v_and_b32_e32 v89, 0xffff0000, v43
	v_lshlrev_b32_e32 v90, 16, v42
	v_and_b32_e32 v91, 0xffff0000, v42
	v_lshlrev_b32_e32 v42, 16, v41
	v_and_b32_e32 v43, 0xffff0000, v41
	v_lshlrev_b32_e32 v92, 16, v40
	v_and_b32_e32 v93, 0xffff0000, v40
	s_waitcnt vmcnt(10)
	v_lshlrev_b32_e32 v40, 16, v47
	v_and_b32_e32 v41, 0xffff0000, v47
	s_waitcnt vmcnt(9)
	v_lshlrev_b32_e32 v28, 16, v51
	v_and_b32_e32 v29, 0xffff0000, v51
	v_lshlrev_b32_e32 v94, 16, v46
	v_and_b32_e32 v95, 0xffff0000, v46
	v_lshlrev_b32_e32 v46, 16, v50
	v_and_b32_e32 v47, 0xffff0000, v50
	v_lshlrev_b32_e32 v50, 16, v45
	v_and_b32_e32 v51, 0xffff0000, v45
	v_lshlrev_b32_e32 v96, 16, v49
	v_and_b32_e32 v97, 0xffff0000, v49
	v_lshlrev_b32_e32 v98, 16, v44
	v_and_b32_e32 v99, 0xffff0000, v44
	v_lshlrev_b32_e32 v44, 16, v48
	v_and_b32_e32 v45, 0xffff0000, v48
	v_mul_f32_e32 v39, 0xbfb8aa3b, v46
	v_mul_f32_e32 v104, 0xbfb8aa3b, v47
	v_mul_f32_e32 v105, 0xbfb8aa3b, v96
	v_mul_f32_e32 v106, 0xbfb8aa3b, v97
	v_mul_f32_e32 v107, 0xbfb8aa3b, v44
	v_mul_f32_e32 v108, 0xbfb8aa3b, v45
	v_mul_f32_e32 v109, 0xbfb8aa3b, v28
	v_mul_f32_e32 v110, 0xbfb8aa3b, v29
	s_waitcnt vmcnt(8)
	v_lshlrev_b32_e32 v48, 16, v55
	v_and_b32_e32 v49, 0xffff0000, v55
	v_lshlrev_b32_e32 v100, 16, v54
	v_and_b32_e32 v101, 0xffff0000, v54
	v_lshlrev_b32_e32 v54, 16, v53
	v_and_b32_e32 v55, 0xffff0000, v53
	v_lshlrev_b32_e32 v102, 16, v52
	v_and_b32_e32 v103, 0xffff0000, v52
	v_exp_f32_e32 v39, v39
	v_exp_f32_e32 v136, v104
	v_exp_f32_e32 v137, v105
	v_exp_f32_e32 v138, v106
	v_exp_f32_e32 v139, v107
	v_exp_f32_e32 v140, v108
	s_waitcnt vmcnt(7)
	v_lshlrev_b32_e32 v52, 16, v59
	v_and_b32_e32 v53, 0xffff0000, v59
	v_lshlrev_b32_e32 v104, 16, v58
	v_and_b32_e32 v105, 0xffff0000, v58
	v_lshlrev_b32_e32 v58, 16, v57
	v_and_b32_e32 v59, 0xffff0000, v57
	v_lshlrev_b32_e32 v106, 16, v56
	v_and_b32_e32 v107, 0xffff0000, v56
	v_exp_f32_e32 v141, v109
	v_exp_f32_e32 v142, v110
	s_waitcnt vmcnt(6)
	v_lshlrev_b32_e32 v56, 16, v63
	v_and_b32_e32 v57, 0xffff0000, v63
	v_lshlrev_b32_e32 v108, 16, v62
	v_and_b32_e32 v109, 0xffff0000, v62
	v_lshlrev_b32_e32 v62, 16, v61
	v_and_b32_e32 v63, 0xffff0000, v61
	v_lshlrev_b32_e32 v110, 16, v60
	v_and_b32_e32 v111, 0xffff0000, v60
	s_waitcnt vmcnt(5)
	v_lshlrev_b32_e32 v60, 16, v67
	v_and_b32_e32 v61, 0xffff0000, v67
	v_lshlrev_b32_e32 v112, 16, v66
	v_and_b32_e32 v113, 0xffff0000, v66
	v_lshlrev_b32_e32 v66, 16, v65
	v_and_b32_e32 v67, 0xffff0000, v65
	v_lshlrev_b32_e32 v114, 16, v64
	v_and_b32_e32 v115, 0xffff0000, v64
	v_mul_f32_e32 v122, 0xbfb8aa3b, v108
	v_mul_f32_e32 v123, 0xbfb8aa3b, v109
	v_mul_f32_e32 v124, 0xbfb8aa3b, v62
	v_mul_f32_e32 v125, 0xbfb8aa3b, v63
	v_mul_f32_e32 v126, 0xbfb8aa3b, v110
	v_mul_f32_e32 v127, 0xbfb8aa3b, v111
	s_waitcnt vmcnt(4)
	v_lshlrev_b32_e32 v64, 16, v71
	v_and_b32_e32 v65, 0xffff0000, v71
	v_lshlrev_b32_e32 v116, 16, v70
	v_and_b32_e32 v117, 0xffff0000, v70
	v_lshlrev_b32_e32 v70, 16, v69
	v_and_b32_e32 v71, 0xffff0000, v69
	v_lshlrev_b32_e32 v118, 16, v68
	v_and_b32_e32 v119, 0xffff0000, v68
	v_mul_f32_e32 v128, 0xbfb8aa3b, v60
	v_mul_f32_e32 v129, 0xbfb8aa3b, v61
	v_mul_f32_e32 v130, 0xbfb8aa3b, v112
	v_mul_f32_e32 v131, 0xbfb8aa3b, v113
	v_mul_f32_e32 v132, 0xbfb8aa3b, v66
	v_mul_f32_e32 v133, 0xbfb8aa3b, v67
	v_mul_f32_e32 v134, 0xbfb8aa3b, v114
	v_mul_f32_e32 v135, 0xbfb8aa3b, v115
	s_waitcnt vmcnt(2)
	v_lshlrev_b32_e32 v68, 16, v79
	v_and_b32_e32 v69, 0xffff0000, v79
	v_lshlrev_b32_e32 v120, 16, v78
	v_and_b32_e32 v121, 0xffff0000, v78
	v_exp_f32_e32 v153, v122
	v_exp_f32_e32 v154, v123
	v_lshlrev_b32_e32 v78, 16, v77
	v_and_b32_e32 v79, 0xffff0000, v77
	v_exp_f32_e32 v155, v124
	v_exp_f32_e32 v156, v125
	v_lshlrev_b32_e32 v122, 16, v76
	v_and_b32_e32 v123, 0xffff0000, v76
	v_exp_f32_e32 v157, v126
	v_exp_f32_e32 v159, v127
	v_lshlrev_b32_e32 v76, 16, v75
	v_and_b32_e32 v77, 0xffff0000, v75
	v_lshlrev_b32_e32 v124, 16, v74
	v_and_b32_e32 v125, 0xffff0000, v74
	v_lshlrev_b32_e32 v74, 16, v73
	v_and_b32_e32 v75, 0xffff0000, v73
	v_lshlrev_b32_e32 v126, 16, v72
	v_and_b32_e32 v127, 0xffff0000, v72
	v_exp_f32_e32 v160, v128
	v_exp_f32_e32 v161, v129
	v_exp_f32_e32 v162, v130
	v_exp_f32_e32 v163, v131
	v_exp_f32_e32 v164, v132
	v_exp_f32_e32 v165, v133
	v_exp_f32_e32 v166, v134
	v_exp_f32_e32 v167, v135
	s_waitcnt vmcnt(0)
	v_lshlrev_b32_e32 v72, 16, v87
	v_and_b32_e32 v73, 0xffff0000, v87
	v_lshlrev_b32_e32 v128, 16, v86
	v_and_b32_e32 v129, 0xffff0000, v86
	v_lshlrev_b32_e32 v86, 16, v85
	v_and_b32_e32 v87, 0xffff0000, v85
	v_lshlrev_b32_e32 v130, 16, v84
	v_and_b32_e32 v131, 0xffff0000, v84
	v_lshlrev_b32_e32 v84, 16, v83
	v_and_b32_e32 v85, 0xffff0000, v83
	v_lshlrev_b32_e32 v132, 16, v82
	v_and_b32_e32 v133, 0xffff0000, v82
	v_lshlrev_b32_e32 v82, 16, v81
	v_and_b32_e32 v83, 0xffff0000, v81
	v_lshlrev_b32_e32 v134, 16, v80
	v_and_b32_e32 v135, 0xffff0000, v80
	v_pk_add_f32 v[54:55], v[74:75], v[54:55]
	v_pk_add_f32 v[74:75], v[126:127], v[102:103]
	v_add_f32_e32 v39, 1.0, v39
	v_pk_add_f32 v[50:51], v[86:87], v[50:51]
	v_add_f32_e32 v126, 1.0, v137
	v_add_f32_e32 v127, 1.0, v138
	v_pk_add_f32 v[86:87], v[130:131], v[98:99]
	v_add_f32_e32 v130, 1.0, v139
	v_add_f32_e32 v131, 1.0, v140
	v_pk_add_f32 v[52:53], v[84:85], v[52:53]
	v_pk_add_f32 v[84:85], v[132:133], v[104:105]
	v_pk_add_f32 v[58:59], v[82:83], v[58:59]
	v_pk_add_f32 v[82:83], v[134:135], v[106:107]
	v_pk_mul_f32 v[104:105], v[74:75], v[74:75]
	v_pk_add_f32 v[42:43], v[78:79], v[42:43]
	v_pk_add_f32 v[78:79], v[122:123], v[92:93]
	v_pk_mul_f32 v[102:103], v[54:55], v[54:55]
	v_rcp_f32_e32 v122, v39
	v_rcp_f32_e32 v126, v126
	v_rcp_f32_e32 v127, v127
	v_rcp_f32_e32 v130, v130
	v_rcp_f32_e32 v131, v131
	v_pk_mul_f32 v[138:139], v[82:83], v[82:83]
	v_add_f32_e32 v39, v104, v105
	v_pk_add_f32 v[48:49], v[76:77], v[48:49]
	v_pk_add_f32 v[76:77], v[124:125], v[100:101]
	v_add_f32_e32 v123, 1.0, v136
	v_pk_mul_f32 v[136:137], v[58:59], v[58:59]
	v_add_f32_e32 v104, v138, v139
	v_add_f32_e32 v39, v102, v39
	v_pk_mul_f32 v[100:101], v[76:77], v[76:77]
	v_add_f32_e32 v105, 1.0, v153
	v_add_f32_e32 v138, 1.0, v154
	v_add_f32_e32 v136, v136, v104
	v_add_f32_e32 v39, v103, v39
	v_pk_mul_f32 v[134:135], v[84:85], v[84:85]
	v_rcp_f32_e32 v104, v105
	v_rcp_f32_e32 v105, v138
	v_add_f32_e32 v136, v137, v136
	v_add_f32_e32 v39, v100, v39
	v_pk_mul_f32 v[98:99], v[48:49], v[48:49]
	v_pk_mul_f32 v[96:97], v[126:127], v[96:97]
	v_pk_mul_f32 v[126:127], v[130:131], v[44:45]
	v_add_f32_e32 v44, v134, v136
	v_add_f32_e32 v39, v101, v39
	v_pk_mul_f32 v[132:133], v[52:53], v[52:53]
	v_add_f32_e32 v44, v135, v44
	v_add_f32_e32 v39, v98, v39
	v_pk_add_f32 v[40:41], v[72:73], v[40:41]
	v_pk_add_f32 v[72:73], v[128:129], v[94:95]
	v_pk_mul_f32 v[94:95], v[78:79], v[78:79]
	v_add_f32_e32 v130, v132, v44
	v_add_f32_e32 v39, v99, v39
	v_pk_mul_f32 v[128:129], v[86:87], v[86:87]
	v_pk_mul_f32 v[44:45], v[104:105], v[108:109]
	v_add_f32_e32 v108, v133, v130
	v_add_f32_e32 v39, v94, v39
	v_pk_mul_f32 v[92:93], v[42:43], v[42:43]
	v_add_f32_e32 v94, v128, v108
	v_add_f32_e32 v39, v95, v39
	v_pk_add_f32 v[80:81], v[120:121], v[90:91]
	v_pk_mul_f32 v[124:125], v[50:51], v[50:51]
	v_add_f32_e32 v94, v129, v94
	v_add_f32_e32 v39, v92, v39
	v_pk_mul_f32 v[90:91], v[80:81], v[80:81]
	v_add_f32_e32 v92, v124, v94
	v_add_f32_e32 v39, v93, v39
	v_pk_add_f32 v[68:69], v[68:69], v[88:89]
	v_pk_mul_f32 v[120:121], v[72:73], v[72:73]
	v_add_f32_e32 v92, v125, v92
	v_add_f32_e32 v39, v90, v39
	v_pk_mul_f32 v[88:89], v[68:69], v[68:69]
	v_add_f32_e32 v90, v120, v92
	v_add_f32_e32 v39, v91, v39
	v_pk_mul_f32 v[106:107], v[40:41], v[40:41]
	v_add_f32_e32 v90, v121, v90
	v_add_f32_e32 v39, v88, v39
	v_add_f32_e32 v88, v106, v90
	v_add_f32_e32 v39, v89, v39
	v_add_f32_e32 v88, v107, v88
	ds_bpermute_b32 v89, v34, v39
	ds_bpermute_b32 v90, v34, v88
	v_mul_f32_e32 v143, 0xbfb8aa3b, v56
	v_mul_f32_e32 v144, 0xbfb8aa3b, v57
	v_mul_f32_e32 v145, 0xbfb8aa3b, v64
	s_waitcnt lgkmcnt(1)
	v_add_f32_e32 v39, v39, v89
	s_waitcnt lgkmcnt(0)
	v_add_f32_e32 v88, v88, v90
	ds_bpermute_b32 v89, v35, v39
	ds_bpermute_b32 v90, v35, v88
	v_mul_f32_e32 v146, 0xbfb8aa3b, v65
	v_mul_f32_e32 v147, 0xbfb8aa3b, v116
	v_mul_f32_e32 v148, 0xbfb8aa3b, v117
	s_waitcnt lgkmcnt(1)
	v_add_f32_e32 v39, v39, v89
	s_waitcnt lgkmcnt(0)
	v_add_f32_e32 v88, v88, v90
	ds_bpermute_b32 v89, v36, v39
	ds_bpermute_b32 v90, v36, v88
	v_mul_f32_e32 v149, 0xbfb8aa3b, v70
	v_mul_f32_e32 v150, 0xbfb8aa3b, v71
	v_mul_f32_e32 v151, 0xbfb8aa3b, v118
	s_waitcnt lgkmcnt(1)
	v_add_f32_e32 v39, v39, v89
	s_waitcnt lgkmcnt(0)
	v_add_f32_e32 v88, v88, v90
	ds_bpermute_b32 v89, v37, v39
	ds_bpermute_b32 v90, v37, v88
	v_mul_f32_e32 v152, 0xbfb8aa3b, v119
	v_exp_f32_e32 v143, v143
	v_exp_f32_e32 v144, v144
	s_waitcnt lgkmcnt(1)
	v_add_f32_e32 v39, v39, v89
	s_waitcnt lgkmcnt(0)
	v_add_f32_e32 v88, v88, v90
	v_fmamk_f32 v39, v39, 0x3b800000, v17
	v_fmamk_f32 v88, v88, 0x3b800000, v17
	v_mul_f32_e32 v89, 0x4f800000, v39
	v_cmp_gt_f32_e64 s[6:7], s37, v39
	v_mul_f32_e32 v90, 0x4f800000, v88
	v_cmp_gt_f32_e32 vcc, s37, v88
	v_cndmask_b32_e64 v39, v39, v89, s[6:7]
	v_sqrt_f32_e32 v89, v39
	v_cndmask_b32_e32 v88, v88, v90, vcc
	v_sqrt_f32_e32 v90, v88
	v_exp_f32_e32 v145, v145
	v_add_u32_e32 v91, -1, v89
	v_add_u32_e32 v92, 1, v89
	v_add_u32_e32 v93, -1, v90
	v_fma_f32 v95, -v91, v89, v39
	v_add_u32_e32 v94, 1, v90
	v_fma_f32 v106, -v92, v89, v39
	v_fma_f32 v107, -v93, v90, v88
	v_cmp_ge_f32_e64 s[8:9], 0, v95
	v_fma_f32 v108, -v94, v90, v88
	v_cmp_lt_f32_e64 s[10:11], 0, v106
	v_cndmask_b32_e64 v89, v89, v91, s[8:9]
	v_cmp_ge_f32_e64 s[8:9], 0, v107
	v_cndmask_b32_e64 v89, v89, v92, s[10:11]
	v_mul_f32_e32 v91, 0x37800000, v89
	v_cndmask_b32_e64 v90, v90, v93, s[8:9]
	v_cmp_lt_f32_e64 s[8:9], 0, v108
	v_cndmask_b32_e64 v89, v89, v91, s[6:7]
	v_cmp_class_f32_e64 s[6:7], v39, v38
	v_cndmask_b32_e64 v90, v90, v94, s[8:9]
	v_mul_f32_e32 v92, 0x37800000, v90
	v_cndmask_b32_e32 v90, v90, v92, vcc
	v_cmp_class_f32_e32 vcc, v88, v38
	v_cndmask_b32_e64 v39, v89, v39, s[6:7]
	v_exp_f32_e32 v146, v146
	v_cndmask_b32_e32 v89, v90, v88, vcc
	v_div_scale_f32 v88, s[6:7], v39, v39, 1.0
	v_div_scale_f32 v91, s[6:7], v89, v89, 1.0
	v_rcp_f32_e32 v93, v88
	v_rcp_f32_e32 v94, v91
	v_exp_f32_e32 v147, v147
	v_exp_f32_e32 v148, v148
	v_fma_f32 v95, -v88, v93, 1.0
	v_exp_f32_e32 v149, v149
	v_exp_f32_e32 v150, v150
	v_exp_f32_e32 v151, v151
	v_exp_f32_e32 v152, v152
	v_div_scale_f32 v90, vcc, 1.0, v39, 1.0
	v_fma_f32 v106, -v91, v94, 1.0
	v_fmac_f32_e32 v93, v95, v93
	v_div_scale_f32 v92, s[6:7], 1.0, v89, 1.0
	v_fmac_f32_e32 v94, v106, v94
	v_mul_f32_e32 v95, v90, v93
	v_mul_f32_e32 v106, v92, v94
	v_fma_f32 v107, -v88, v95, v90
	v_add_f32_e32 v140, 1.0, v141
	v_add_f32_e32 v141, 1.0, v142
	v_add_f32_e32 v139, 1.0, v155
	v_add_f32_e32 v142, 1.0, v156
	v_add_f32_e32 v153, 1.0, v157
	v_add_f32_e32 v154, 1.0, v159
	v_add_f32_e32 v155, 1.0, v160
	v_add_f32_e32 v156, 1.0, v161
	v_add_f32_e32 v157, 1.0, v162
	v_add_f32_e32 v159, 1.0, v163
	v_add_f32_e32 v160, 1.0, v164
	v_add_f32_e32 v161, 1.0, v165
	v_add_f32_e32 v162, 1.0, v166
	v_add_f32_e32 v163, 1.0, v167
	v_add_f32_e32 v102, 1.0, v143
	v_add_f32_e32 v164, 1.0, v144
	v_fma_f32 v108, -v91, v106, v92
	v_fmac_f32_e32 v95, v107, v93
	v_rcp_f32_e32 v123, v123
	v_add_f32_e32 v165, 1.0, v145
	v_add_f32_e32 v166, 1.0, v146
	v_add_f32_e32 v167, 1.0, v147
	v_add_f32_e32 v168, 1.0, v148
	v_add_f32_e32 v169, 1.0, v149
	v_add_f32_e32 v170, 1.0, v150
	v_add_f32_e32 v171, 1.0, v151
	v_add_f32_e32 v172, 1.0, v152
	v_rcp_f32_e32 v138, v139
	v_rcp_f32_e32 v139, v142
	v_rcp_f32_e32 v144, v155
	v_rcp_f32_e32 v145, v156
	v_rcp_f32_e32 v146, v157
	v_rcp_f32_e32 v147, v159
	v_rcp_f32_e32 v148, v160
	v_rcp_f32_e32 v149, v161
	v_rcp_f32_e32 v150, v162
	v_rcp_f32_e32 v151, v163
	v_rcp_f32_e32 v102, v102
	v_rcp_f32_e32 v103, v164
	v_fmac_f32_e32 v106, v108, v94
	v_fma_f32 v88, -v88, v95, v90
	v_rcp_f32_e32 v142, v153
	v_rcp_f32_e32 v143, v154
	v_rcp_f32_e32 v152, v165
	v_rcp_f32_e32 v153, v166
	v_rcp_f32_e32 v154, v167
	v_rcp_f32_e32 v155, v168
	v_rcp_f32_e32 v156, v169
	v_rcp_f32_e32 v157, v170
	v_rcp_f32_e32 v160, v171
	v_rcp_f32_e32 v161, v172
	v_fma_f32 v90, -v91, v106, v92
	v_div_fmas_f32 v88, v88, v93, v95
	s_mov_b64 vcc, s[6:7]
	v_rcp_f32_e32 v140, v140
	v_rcp_f32_e32 v141, v141
	v_div_fixup_f32 v88, v88, v39, 1.0
	v_div_fmas_f32 v39, v90, v94, v106
	v_pk_mul_f32 v[74:75], v[74:75], v[88:89] op_sel_hi:[1,0]
	v_pk_mul_f32 v[54:55], v[54:55], v[88:89] op_sel_hi:[1,0]
	v_pk_mul_f32 v[76:77], v[76:77], v[88:89] op_sel_hi:[1,0]
	v_pk_mul_f32 v[48:49], v[48:49], v[88:89] op_sel_hi:[1,0]
	v_pk_mul_f32 v[78:79], v[78:79], v[88:89] op_sel_hi:[1,0]
	v_pk_mul_f32 v[42:43], v[42:43], v[88:89] op_sel_hi:[1,0]
	v_pk_mul_f32 v[80:81], v[80:81], v[88:89] op_sel_hi:[1,0]
	v_pk_mul_f32 v[68:69], v[68:69], v[88:89] op_sel_hi:[1,0]
	v_div_fixup_f32 v88, v39, v89, 1.0
	v_pk_mul_f32 v[122:123], v[122:123], v[46:47]
	v_pk_mul_f32 v[46:47], v[138:139], v[62:63]
	v_pk_mul_f32 v[60:61], v[144:145], v[60:61]
	v_pk_mul_f32 v[100:101], v[146:147], v[112:113]
	v_pk_mul_f32 v[66:67], v[148:149], v[66:67]
	v_pk_mul_f32 v[104:105], v[150:151], v[114:115]
	v_pk_mul_f32 v[56:57], v[102:103], v[56:57]
	v_pk_mul_f32 v[74:75], v[12:13], v[74:75]
	v_pk_mul_f32 v[54:55], v[14:15], v[54:55]
	v_pk_mul_f32 v[76:77], v[8:9], v[76:77]
	v_pk_mul_f32 v[48:49], v[10:11], v[48:49]
	v_pk_mul_f32 v[42:43], v[6:7], v[42:43]
	v_pk_mul_f32 v[68:69], v[2:3], v[68:69]
	v_pk_mul_f32 v[82:83], v[82:83], v[88:89] op_sel_hi:[1,0]
	v_pk_mul_f32 v[58:59], v[58:59], v[88:89] op_sel_hi:[1,0]
	v_pk_mul_f32 v[84:85], v[84:85], v[88:89] op_sel_hi:[1,0]
	v_pk_mul_f32 v[52:53], v[52:53], v[88:89] op_sel_hi:[1,0]
	v_pk_mul_f32 v[62:63], v[142:143], v[110:111]
	v_pk_mul_f32 v[64:65], v[152:153], v[64:65]
	v_pk_mul_f32 v[98:99], v[154:155], v[116:117]
	v_pk_mul_f32 v[70:71], v[156:157], v[70:71]
	v_pk_mul_f32 v[102:103], v[160:161], v[118:119]
	v_pk_mul_f32 v[78:79], v[4:5], v[78:79]
	v_pk_mul_f32 v[80:81], v[0:1], v[80:81]
	v_pk_mul_f32 v[86:87], v[86:87], v[88:89] op_sel_hi:[1,0]
	v_pk_mul_f32 v[50:51], v[50:51], v[88:89] op_sel_hi:[1,0]
	v_pk_mul_f32 v[72:73], v[72:73], v[88:89] op_sel_hi:[1,0]
	v_pk_mul_f32 v[40:41], v[40:41], v[88:89] op_sel_hi:[1,0]
	v_pk_mul_f32 v[74:75], v[104:105], v[74:75]
	v_pk_mul_f32 v[54:55], v[66:67], v[54:55]
	v_pk_mul_f32 v[66:67], v[100:101], v[76:77]
	v_pk_mul_f32 v[48:49], v[60:61], v[48:49]
	v_pk_mul_f32 v[46:47], v[46:47], v[42:43]
	v_pk_mul_f32 v[56:57], v[56:57], v[68:69]
	v_pk_mul_f32 v[68:69], v[12:13], v[82:83]
	v_pk_mul_f32 v[58:59], v[14:15], v[58:59]
	v_pk_mul_f32 v[76:77], v[8:9], v[84:85]
	v_pk_mul_f32 v[52:53], v[10:11], v[52:53]
	v_pk_mul_f32 v[28:29], v[140:141], v[28:29]
	v_pk_mul_f32 v[60:61], v[62:63], v[78:79]
	v_pk_mul_f32 v[62:63], v[44:45], v[80:81]
	v_pk_mul_f32 v[78:79], v[4:5], v[86:87]
	v_pk_mul_f32 v[50:51], v[6:7], v[50:51]
	v_pk_mul_f32 v[72:73], v[0:1], v[72:73]
	v_pk_mul_f32 v[80:81], v[2:3], v[40:41]
	v_cvt_pk_bf16_f32 v40, v74, v75
	v_cvt_pk_bf16_f32 v41, v54, v55
	v_cvt_pk_bf16_f32 v42, v66, v67
	v_cvt_pk_bf16_f32 v43, v48, v49
	v_cvt_pk_bf16_f32 v45, v46, v47
	v_cvt_pk_bf16_f32 v47, v56, v57
	v_pk_mul_f32 v[48:49], v[102:103], v[68:69]
	v_pk_mul_f32 v[54:55], v[70:71], v[58:59]
	v_pk_mul_f32 v[56:57], v[98:99], v[76:77]
	v_pk_mul_f32 v[52:53], v[64:65], v[52:53]
	v_cvt_pk_bf16_f32 v44, v60, v61
	v_cvt_pk_bf16_f32 v46, v62, v63
	v_pk_mul_f32 v[58:59], v[126:127], v[78:79]
	v_pk_mul_f32 v[50:51], v[96:97], v[50:51]
	v_pk_mul_f32 v[60:61], v[122:123], v[72:73]
	v_pk_mul_f32 v[62:63], v[28:29], v[80:81]
	global_store_dwordx4 v[26:27], v[40:43], off offset:-4096
	global_store_dwordx4 v[30:31], v[44:47], off offset:16
	v_cvt_pk_bf16_f32 v28, v48, v49
	v_cvt_pk_bf16_f32 v29, v54, v55
	v_cvt_pk_bf16_f32 v30, v56, v57
	v_cvt_pk_bf16_f32 v31, v52, v53
	v_cvt_pk_bf16_f32 v40, v58, v59
	v_cvt_pk_bf16_f32 v41, v50, v51
	v_cvt_pk_bf16_f32 v42, v60, v61
	v_cvt_pk_bf16_f32 v43, v62, v63
	global_store_dwordx4 v[26:27], v[28:31], off
	global_store_dwordx4 v[26:27], v[40:43], off offset:16
	s_andn2_b64 exec, exec, s[22:23]
	s_cbranch_execnz .LBB0_409
